# prologue weight-conversion loops also unrolled to 32 loads in flight per item
# baseline (speedup 1.0000x reference)
; #define LAS __attribute__((address_space(3)))
; __device__ __forceinline__ void transpose_item(const float* __restrict__ W, int K, int N, bf16* __restrict__ WT, int mode, LAS float* scr, int item, int lane) {
;     const int nblk = N / 32, kb = item / nblk, nb = item % nblk, k0 = 64 * kb, n0 = 32 * nb;
; #pragma unroll 8
;     for (int i = 0; i < 32; ++i) { const int kk = 2 * i + (lane >> 5); scr[kk * 33 + (lane & 31)] = __builtin_nontemporal_load(W + (size_t)(k0 + kk) * N + n0 + (lane & 31)); }
;     asm volatile("s_waitcnt lgkmcnt(0)" ::: "memory");
; __device__ __forceinline__ void convert_weights(ArgP A, unsigned char* lds_g, int gw, int NGW, int l0, int l1, int lane, int wave) {
;     ...
;     for (int it = l0 * PER_L + gw; it < l1 * PER_L; it += NGW) {
;         const int l = it / PER_L; int r = it - l * PER_L;
;         if (r < I_IN) { transpose_item(A->w_in + (size_t)l * DM * INW, DM, INW, (bf16*)(ws + WS_WIN) + (size_t)l * INW * DM, 1, scr, r, lane); continue; } r -= I_IN;
;         if (r < I_OUT) { transpose_item(A->w_out + (size_t)l * DM * DM, DM, DM, (bf16*)(ws + WS_WOUT) + (size_t)l * DM * DM, 0, scr, r, lane); continue; } r -= I_OUT;
;         if (r < I_F1) { transpose_item(A->w_ffn_in + (size_t)l * DM * FF2, DM, FF2, (bf16*)(ws + WS_WF1) + (size_t)l * FF2 * DM, 2, scr, r, lane); continue; } r -= I_F1;
;         transpose_item(A->w_ffn_out + (size_t)l * FFH * DM, FFH, DM, (bf16*)(ws + WS_WF2) + (size_t)l * DM * FFH, 0, scr, r, lane);
;     }
.LBB0_381:
	v_add_u32_e32 v15, s3, v13
	v_add_u32_e32 v16, 0xffffdf00, v15
	v_add_u32_e32 v18, 0xffffdf02, v15
	v_add_u32_e32 v20, 0xffffdf04, v15
	v_add_u32_e32 v22, 0xffffdf06, v15
	v_add_u32_e32 v24, 0xffffdf08, v15
	v_add_u32_e32 v42, 0xffffdf0a, v15
	v_add_u32_e32 v44, 0xffffdf0c, v15
	v_add_u32_e32 v46, 0xffffdf0e, v15
	v_ashrrev_i32_e32 v17, 31, v16
	v_ashrrev_i32_e32 v19, 31, v18
	v_ashrrev_i32_e32 v21, 31, v20
	v_ashrrev_i32_e32 v23, 31, v22
	v_ashrrev_i32_e32 v25, 31, v24
	v_ashrrev_i32_e32 v43, 31, v42
	v_ashrrev_i32_e32 v45, 31, v44
	v_ashrrev_i32_e32 v47, 31, v46
	v_lshlrev_b64 v[16:17], 12, v[16:17]
	v_lshlrev_b64 v[18:19], 12, v[18:19]
	v_lshlrev_b64 v[20:21], 12, v[20:21]
	v_lshlrev_b64 v[22:23], 12, v[22:23]
	v_lshlrev_b64 v[24:25], 12, v[24:25]
	v_lshlrev_b64 v[42:43], 12, v[42:43]
	v_lshlrev_b64 v[44:45], 12, v[44:45]
	v_lshlrev_b64 v[46:47], 12, v[46:47]
	v_lshl_add_u64 v[16:17], v[10:11], 0, v[16:17]
	v_lshl_add_u64 v[18:19], v[10:11], 0, v[18:19]
	v_lshl_add_u64 v[20:21], v[10:11], 0, v[20:21]
	v_lshl_add_u64 v[22:23], v[10:11], 0, v[22:23]
	v_lshl_add_u64 v[24:25], v[10:11], 0, v[24:25]
	v_lshl_add_u64 v[42:43], v[10:11], 0, v[42:43]
	v_lshl_add_u64 v[44:45], v[10:11], 0, v[44:45]
	v_lshl_add_u64 v[46:47], v[10:11], 0, v[46:47]
	global_load_dword v172, v[16:17], off nt
	s_nop 0
	global_load_dword v173, v[18:19], off nt
	global_load_dword v174, v[20:21], off nt
	s_nop 0
	global_load_dword v175, v[22:23], off nt
	global_load_dword v176, v[24:25], off nt
	global_load_dword v177, v[42:43], off nt
	global_load_dword v178, v[44:45], off nt
	s_nop 0
	global_load_dword v179, v[46:47], off nt
	s_add_i32 s3, s3, 16
	v_add_u32_e32 v15, s3, v13
	v_add_u32_e32 v16, 0xffffdf00, v15
	v_add_u32_e32 v18, 0xffffdf02, v15
	v_add_u32_e32 v20, 0xffffdf04, v15
	v_add_u32_e32 v22, 0xffffdf06, v15
	v_add_u32_e32 v24, 0xffffdf08, v15
	v_add_u32_e32 v42, 0xffffdf0a, v15
	v_add_u32_e32 v44, 0xffffdf0c, v15
	v_add_u32_e32 v46, 0xffffdf0e, v15
	v_ashrrev_i32_e32 v17, 31, v16
	v_ashrrev_i32_e32 v19, 31, v18
	v_ashrrev_i32_e32 v21, 31, v20
	v_ashrrev_i32_e32 v23, 31, v22
	v_ashrrev_i32_e32 v25, 31, v24
	v_ashrrev_i32_e32 v43, 31, v42
	v_ashrrev_i32_e32 v45, 31, v44
	v_ashrrev_i32_e32 v47, 31, v46
	v_lshlrev_b64 v[16:17], 12, v[16:17]
	v_lshlrev_b64 v[18:19], 12, v[18:19]
	v_lshlrev_b64 v[20:21], 12, v[20:21]
	v_lshlrev_b64 v[22:23], 12, v[22:23]
	v_lshlrev_b64 v[24:25], 12, v[24:25]
	v_lshlrev_b64 v[42:43], 12, v[42:43]
	v_lshlrev_b64 v[44:45], 12, v[44:45]
	v_lshlrev_b64 v[46:47], 12, v[46:47]
	v_lshl_add_u64 v[16:17], v[10:11], 0, v[16:17]
	v_lshl_add_u64 v[18:19], v[10:11], 0, v[18:19]
	v_lshl_add_u64 v[20:21], v[10:11], 0, v[20:21]
	v_lshl_add_u64 v[22:23], v[10:11], 0, v[22:23]
	v_lshl_add_u64 v[24:25], v[10:11], 0, v[24:25]
	v_lshl_add_u64 v[42:43], v[10:11], 0, v[42:43]
	v_lshl_add_u64 v[44:45], v[10:11], 0, v[44:45]
	v_lshl_add_u64 v[46:47], v[10:11], 0, v[46:47]
	global_load_dword v180, v[16:17], off nt
	s_nop 0
	global_load_dword v181, v[18:19], off nt
	global_load_dword v182, v[20:21], off nt
	s_nop 0
	global_load_dword v183, v[22:23], off nt
	global_load_dword v184, v[24:25], off nt
	global_load_dword v185, v[42:43], off nt
	global_load_dword v186, v[44:45], off nt
	s_nop 0
	global_load_dword v187, v[46:47], off nt
	s_add_i32 s3, s3, 16
	v_add_u32_e32 v15, s3, v13
	v_add_u32_e32 v16, 0xffffdf00, v15
	v_add_u32_e32 v18, 0xffffdf02, v15
	v_add_u32_e32 v20, 0xffffdf04, v15
	v_add_u32_e32 v22, 0xffffdf06, v15
	v_add_u32_e32 v24, 0xffffdf08, v15
	v_add_u32_e32 v42, 0xffffdf0a, v15
	v_add_u32_e32 v44, 0xffffdf0c, v15
	v_add_u32_e32 v46, 0xffffdf0e, v15
	v_ashrrev_i32_e32 v17, 31, v16
	v_ashrrev_i32_e32 v19, 31, v18
	v_ashrrev_i32_e32 v21, 31, v20
	v_ashrrev_i32_e32 v23, 31, v22
	v_ashrrev_i32_e32 v25, 31, v24
	v_ashrrev_i32_e32 v43, 31, v42
	v_ashrrev_i32_e32 v45, 31, v44
	v_ashrrev_i32_e32 v47, 31, v46
	v_lshlrev_b64 v[16:17], 12, v[16:17]
	v_lshlrev_b64 v[18:19], 12, v[18:19]
	v_lshlrev_b64 v[20:21], 12, v[20:21]
	v_lshlrev_b64 v[22:23], 12, v[22:23]
	v_lshlrev_b64 v[24:25], 12, v[24:25]
	v_lshlrev_b64 v[42:43], 12, v[42:43]
	v_lshlrev_b64 v[44:45], 12, v[44:45]
	v_lshlrev_b64 v[46:47], 12, v[46:47]
	v_lshl_add_u64 v[16:17], v[10:11], 0, v[16:17]
	v_lshl_add_u64 v[18:19], v[10:11], 0, v[18:19]
	v_lshl_add_u64 v[20:21], v[10:11], 0, v[20:21]
	v_lshl_add_u64 v[22:23], v[10:11], 0, v[22:23]
	v_lshl_add_u64 v[24:25], v[10:11], 0, v[24:25]
	v_lshl_add_u64 v[42:43], v[10:11], 0, v[42:43]
	v_lshl_add_u64 v[44:45], v[10:11], 0, v[44:45]
	v_lshl_add_u64 v[46:47], v[10:11], 0, v[46:47]
	global_load_dword v188, v[16:17], off nt
	s_nop 0
	global_load_dword v189, v[18:19], off nt
	global_load_dword v190, v[20:21], off nt
	s_nop 0
	global_load_dword v191, v[22:23], off nt
	global_load_dword v192, v[24:25], off nt
	global_load_dword v193, v[42:43], off nt
	global_load_dword v194, v[44:45], off nt
	s_nop 0
	global_load_dword v195, v[46:47], off nt
	s_add_i32 s3, s3, 16
	v_add_u32_e32 v15, s3, v13
	v_add_u32_e32 v16, 0xffffdf00, v15
	v_add_u32_e32 v18, 0xffffdf02, v15
	v_add_u32_e32 v20, 0xffffdf04, v15
	v_add_u32_e32 v22, 0xffffdf06, v15
	v_add_u32_e32 v24, 0xffffdf08, v15
	v_add_u32_e32 v42, 0xffffdf0a, v15
	v_add_u32_e32 v44, 0xffffdf0c, v15
	v_add_u32_e32 v46, 0xffffdf0e, v15
	v_ashrrev_i32_e32 v17, 31, v16
	v_ashrrev_i32_e32 v19, 31, v18
	v_ashrrev_i32_e32 v21, 31, v20
	v_ashrrev_i32_e32 v23, 31, v22
	v_ashrrev_i32_e32 v25, 31, v24
	v_ashrrev_i32_e32 v43, 31, v42
	v_ashrrev_i32_e32 v45, 31, v44
	v_ashrrev_i32_e32 v47, 31, v46
	v_lshlrev_b64 v[16:17], 12, v[16:17]
	v_lshlrev_b64 v[18:19], 12, v[18:19]
	v_lshlrev_b64 v[20:21], 12, v[20:21]
	v_lshlrev_b64 v[22:23], 12, v[22:23]
	v_lshlrev_b64 v[24:25], 12, v[24:25]
	v_lshlrev_b64 v[42:43], 12, v[42:43]
	v_lshlrev_b64 v[44:45], 12, v[44:45]
	v_lshlrev_b64 v[46:47], 12, v[46:47]
	v_lshl_add_u64 v[16:17], v[10:11], 0, v[16:17]
	v_lshl_add_u64 v[18:19], v[10:11], 0, v[18:19]
	v_lshl_add_u64 v[20:21], v[10:11], 0, v[20:21]
	v_lshl_add_u64 v[22:23], v[10:11], 0, v[22:23]
	v_lshl_add_u64 v[24:25], v[10:11], 0, v[24:25]
	v_lshl_add_u64 v[42:43], v[10:11], 0, v[42:43]
	v_lshl_add_u64 v[44:45], v[10:11], 0, v[44:45]
	v_lshl_add_u64 v[46:47], v[10:11], 0, v[46:47]
	global_load_dword v196, v[16:17], off nt
	s_nop 0
	global_load_dword v197, v[18:19], off nt
	global_load_dword v198, v[20:21], off nt
	s_nop 0
	global_load_dword v199, v[22:23], off nt
	global_load_dword v218, v[24:25], off nt
	global_load_dword v219, v[42:43], off nt
	global_load_dword v220, v[44:45], off nt
	s_nop 0
	global_load_dword v221, v[46:47], off nt
	s_add_i32 s3, s3, 16
	v_add_u32_e32 v23, 0x400, v14
	s_waitcnt vmcnt(30)
; #define LAS __attribute__((address_space(3)))
; __device__ __forceinline__ unsigned pk2(float lo, float hi) { return pg8::cvt_pk_bf16(lo, hi); }
; __device__ __forceinline__ void transpose_item(const float* __restrict__ W, int K, int N, bf16* __restrict__ WT, int mode, LAS float* scr, int item, int lane) {
;     ...
;     for (int i = 0; i < 32; ++i) { const int kk = 2 * i + (lane >> 5); scr[kk * 33 + (lane & 31)] = __builtin_nontemporal_load(W + (size_t)(k0 + kk) * N + n0 + (lane & 31)); }
;     asm volatile("s_waitcnt lgkmcnt(0)" ::: "memory");
;     const int c = lane & 7; const int r0 = rowmap(mode, n0);
; #pragma unroll
;     for (int j = 0; j < 4; ++j) { const int n = (lane >> 3) + 8 * j; const LAS float* s = scr + (8 * c) * 33 + n;
;         u32x4 o; o.x = pk2(s[0 * 33], s[1 * 33]); o.y = pk2(s[2 * 33], s[3 * 33]); o.z = pk2(s[4 * 33], s[5 * 33]); o.w = pk2(s[6 * 33], s[7 * 33]);
;         *(u32x4*)(WT + (size_t)(r0 + n) * K + k0 + 8 * c) = o; }
;     asm volatile("s_waitcnt lgkmcnt(0)" ::: "memory");
	ds_write2_b32 v14, v172, v173 offset1:66
	s_waitcnt vmcnt(28)
	ds_write2_b32 v14, v174, v175 offset0:132 offset1:198
	s_waitcnt vmcnt(26)
	ds_write2_b32 v23, v176, v177 offset0:8 offset1:74
	s_waitcnt vmcnt(24)
	ds_write2_b32 v23, v178, v179 offset0:140 offset1:206
	v_add_u32_e32 v14, 0x840, v14
	v_add_u32_e32 v23, 0x400, v14
	s_waitcnt vmcnt(22)
	ds_write2_b32 v14, v180, v181 offset1:66
	s_waitcnt vmcnt(20)
	ds_write2_b32 v14, v182, v183 offset0:132 offset1:198
	s_waitcnt vmcnt(18)
	ds_write2_b32 v23, v184, v185 offset0:8 offset1:74
	s_waitcnt vmcnt(16)
	ds_write2_b32 v23, v186, v187 offset0:140 offset1:206
	v_add_u32_e32 v14, 0x840, v14
	v_add_u32_e32 v23, 0x400, v14
	s_waitcnt vmcnt(14)
	ds_write2_b32 v14, v188, v189 offset1:66
	s_waitcnt vmcnt(12)
	ds_write2_b32 v14, v190, v191 offset0:132 offset1:198
	s_waitcnt vmcnt(10)
	ds_write2_b32 v23, v192, v193 offset0:8 offset1:74
	s_waitcnt vmcnt(8)
	ds_write2_b32 v23, v194, v195 offset0:140 offset1:206
	v_add_u32_e32 v14, 0x840, v14
	v_add_u32_e32 v23, 0x400, v14
	s_waitcnt vmcnt(6)
	ds_write2_b32 v14, v196, v197 offset1:66
	s_waitcnt vmcnt(4)
	ds_write2_b32 v14, v198, v199 offset0:132 offset1:198
	s_waitcnt vmcnt(2)
	ds_write2_b32 v23, v218, v219 offset0:8 offset1:74
	s_waitcnt vmcnt(0)
	ds_write2_b32 v23, v220, v221 offset0:140 offset1:206
	v_add_u32_e32 v14, 0x840, v14
	s_waitcnt lgkmcnt(0)
	ds_read2_b32 v[10:11], v27 offset1:33
	s_waitcnt lgkmcnt(0)
	v_cvt_pk_bf16_f32 v10, v10, v11
	ds_read2_b32 v[14:15], v27 offset0:66 offset1:99
	v_and_b32_e32 v16, 0xffffffc0, v12
	s_waitcnt lgkmcnt(0)
	v_cvt_pk_bf16_f32 v11, v14, v15
	v_mul_hi_i32_i24_e32 v15, 0x580000, v8
	v_mul_i32_i24_e32 v14, 0x580000, v8
	v_or_b32_e32 v8, v9, v26
	v_add_u32_e32 v160, 0xffffdf00, v16
	v_lshl_add_u64 v[14:15], s[6:7], 0, v[14:15]
	v_mul_u32_u24_e32 v8, 0xb00, v8
	v_lshl_add_u64 v[14:15], v[160:161], 1, v[14:15]
	v_lshlrev_b32_e32 v160, 1, v4
	ds_read2_b32 v[12:13], v27 offset0:132 offset1:165
	v_lshl_add_u64 v[14:15], v[14:15], 0, v[160:161]
	v_lshlrev_b32_e32 v160, 1, v8
	s_waitcnt lgkmcnt(0)
	v_cvt_pk_bf16_f32 v12, v12, v13
	ds_read2_b32 v[16:17], v27 offset0:198 offset1:231
	s_waitcnt lgkmcnt(0)
	v_cvt_pk_bf16_f32 v13, v16, v17
	v_lshl_add_u64 v[18:19], v[14:15], 0, v[160:161]
	v_or_b32_e32 v8, v9, v28
	ds_read2_b32 v[16:17], v27 offset0:8 offset1:41
	global_store_dwordx4 v[18:19], v[10:13], off
	v_mul_u32_u24_e32 v8, 0xb00, v8
	v_lshlrev_b32_e32 v160, 1, v8
	s_waitcnt lgkmcnt(0)
	v_cvt_pk_bf16_f32 v10, v16, v17
	ds_read2_b32 v[12:13], v27 offset0:74 offset1:107
	s_waitcnt lgkmcnt(0)
	v_cvt_pk_bf16_f32 v11, v12, v13
	ds_read2_b32 v[12:13], v27 offset0:140 offset1:173
	s_waitcnt lgkmcnt(0)
	v_cvt_pk_bf16_f32 v12, v12, v13
	ds_read2_b32 v[16:17], v27 offset0:206 offset1:239
	s_waitcnt lgkmcnt(0)
	v_cvt_pk_bf16_f32 v13, v16, v17
	v_lshl_add_u64 v[18:19], v[14:15], 0, v[160:161]
	v_or_b32_e32 v8, v9, v29
	ds_read2_b32 v[16:17], v27 offset0:16 offset1:49
	global_store_dwordx4 v[18:19], v[10:13], off
	v_mul_u32_u24_e32 v8, 0xb00, v8
	v_lshlrev_b32_e32 v160, 1, v8
	s_waitcnt lgkmcnt(0)
	v_cvt_pk_bf16_f32 v10, v16, v17
	ds_read2_b32 v[12:13], v27 offset0:82 offset1:115
	s_waitcnt lgkmcnt(0)
	v_cvt_pk_bf16_f32 v11, v12, v13
	ds_read2_b32 v[12:13], v27 offset0:148 offset1:181
	v_or_b32_e32 v8, v9, v30
	s_waitcnt lgkmcnt(0)
	v_cvt_pk_bf16_f32 v12, v12, v13
	ds_read2_b32 v[16:17], v27 offset0:214 offset1:247
	s_waitcnt lgkmcnt(0)
	v_cvt_pk_bf16_f32 v13, v16, v17
	v_lshl_add_u64 v[18:19], v[14:15], 0, v[160:161]
	v_mul_u32_u24_e32 v8, 0xb00, v8
	ds_read2_b32 v[16:17], v27 offset0:24 offset1:57
	global_store_dwordx4 v[18:19], v[10:13], off
	v_lshlrev_b32_e32 v160, 1, v8
	v_lshl_add_u64 v[8:9], v[14:15], 0, v[160:161]
	s_waitcnt lgkmcnt(0)
	v_cvt_pk_bf16_f32 v10, v16, v17
	ds_read2_b32 v[12:13], v27 offset0:90 offset1:123
	s_waitcnt lgkmcnt(0)
	v_cvt_pk_bf16_f32 v11, v12, v13
	ds_read2_b32 v[12:13], v27 offset0:156 offset1:189
	s_waitcnt lgkmcnt(0)
	v_cvt_pk_bf16_f32 v12, v12, v13
	ds_read2_b32 v[16:17], v27 offset0:222 offset1:255
	s_waitcnt lgkmcnt(0)
	v_cvt_pk_bf16_f32 v13, v16, v17
	global_store_dwordx4 v[8:9], v[10:13], off
	s_waitcnt lgkmcnt(0)

; __device__ __forceinline__ void transpose_item(const float* __restrict__ W, int K, int N, bf16* __restrict__ WT, int mode, LAS float* scr, int item, int lane) {
;     const int nblk = N / 32, kb = item / nblk, nb = item % nblk, k0 = 64 * kb, n0 = 32 * nb;
; #pragma unroll 8
;     for (int i = 0; i < 32; ++i) { const int kk = 2 * i + (lane >> 5); scr[kk * 33 + (lane & 31)] = __builtin_nontemporal_load(W + (size_t)(k0 + kk) * N + n0 + (lane & 31)); }
;     asm volatile("s_waitcnt lgkmcnt(0)" ::: "memory");
.LBB0_385:
	v_lshl_add_u64 v[44:45], v[24:25], 0, s[22:23]
	v_lshl_add_u64 v[46:47], v[22:23], 0, s[22:23]
	v_lshl_add_u64 v[48:49], v[20:21], 0, s[22:23]
	v_lshl_add_u64 v[50:51], v[18:19], 0, s[22:23]
	v_lshl_add_u64 v[52:53], v[16:17], 0, s[22:23]
	v_lshl_add_u64 v[54:55], v[14:15], 0, s[22:23]
	v_lshl_add_u64 v[56:57], v[12:13], 0, s[22:23]
	v_lshl_add_u64 v[58:59], v[10:11], 0, s[22:23]
	global_load_dword v172, v[44:45], off nt
	s_nop 0
	global_load_dword v173, v[46:47], off nt
	s_nop 0
	global_load_dword v174, v[48:49], off nt
	global_load_dword v175, v[50:51], off nt
	s_nop 0
	global_load_dword v176, v[52:53], off nt
	global_load_dword v177, v[54:55], off nt
	global_load_dword v178, v[56:57], off nt
	global_load_dword v179, v[58:59], off nt
	s_add_u32 s22, s22, 0x58000
	s_addc_u32 s23, s23, 0
	v_lshl_add_u64 v[44:45], v[24:25], 0, s[22:23]
	v_lshl_add_u64 v[46:47], v[22:23], 0, s[22:23]
	v_lshl_add_u64 v[48:49], v[20:21], 0, s[22:23]
	v_lshl_add_u64 v[50:51], v[18:19], 0, s[22:23]
	v_lshl_add_u64 v[52:53], v[16:17], 0, s[22:23]
	v_lshl_add_u64 v[54:55], v[14:15], 0, s[22:23]
	v_lshl_add_u64 v[56:57], v[12:13], 0, s[22:23]
	v_lshl_add_u64 v[58:59], v[10:11], 0, s[22:23]
	global_load_dword v180, v[44:45], off nt
	s_nop 0
	global_load_dword v181, v[46:47], off nt
	s_nop 0
	global_load_dword v182, v[48:49], off nt
	global_load_dword v183, v[50:51], off nt
	s_nop 0
	global_load_dword v184, v[52:53], off nt
	global_load_dword v185, v[54:55], off nt
	global_load_dword v186, v[56:57], off nt
	global_load_dword v187, v[58:59], off nt
	s_add_u32 s22, s22, 0x58000
	s_addc_u32 s23, s23, 0
	v_lshl_add_u64 v[44:45], v[24:25], 0, s[22:23]
	v_lshl_add_u64 v[46:47], v[22:23], 0, s[22:23]
	v_lshl_add_u64 v[48:49], v[20:21], 0, s[22:23]
	v_lshl_add_u64 v[50:51], v[18:19], 0, s[22:23]
	v_lshl_add_u64 v[52:53], v[16:17], 0, s[22:23]
	v_lshl_add_u64 v[54:55], v[14:15], 0, s[22:23]
	v_lshl_add_u64 v[56:57], v[12:13], 0, s[22:23]
	v_lshl_add_u64 v[58:59], v[10:11], 0, s[22:23]
	global_load_dword v188, v[44:45], off nt
	s_nop 0
	global_load_dword v189, v[46:47], off nt
	s_nop 0
	global_load_dword v190, v[48:49], off nt
	global_load_dword v191, v[50:51], off nt
	s_nop 0
	global_load_dword v192, v[52:53], off nt
	global_load_dword v193, v[54:55], off nt
	global_load_dword v194, v[56:57], off nt
	global_load_dword v195, v[58:59], off nt
	s_add_u32 s22, s22, 0x58000
	s_addc_u32 s23, s23, 0
	v_lshl_add_u64 v[44:45], v[24:25], 0, s[22:23]
	v_lshl_add_u64 v[46:47], v[22:23], 0, s[22:23]
	v_lshl_add_u64 v[48:49], v[20:21], 0, s[22:23]
	v_lshl_add_u64 v[50:51], v[18:19], 0, s[22:23]
	v_lshl_add_u64 v[52:53], v[16:17], 0, s[22:23]
	v_lshl_add_u64 v[54:55], v[14:15], 0, s[22:23]
	v_lshl_add_u64 v[56:57], v[12:13], 0, s[22:23]
	v_lshl_add_u64 v[58:59], v[10:11], 0, s[22:23]
	global_load_dword v196, v[44:45], off nt
	s_nop 0
	global_load_dword v197, v[46:47], off nt
	s_nop 0
	global_load_dword v198, v[48:49], off nt
	global_load_dword v199, v[50:51], off nt
	s_nop 0
	global_load_dword v218, v[52:53], off nt
	global_load_dword v219, v[54:55], off nt
	global_load_dword v220, v[56:57], off nt
	global_load_dword v221, v[58:59], off nt
	s_add_u32 s22, s22, 0x58000
	s_addc_u32 s23, s23, 0
	v_add_u32_e32 v52, 0x400, v43
	s_waitcnt vmcnt(30)
	ds_write2_b32 v43, v172, v173 offset1:66
	s_waitcnt vmcnt(28)
	ds_write2_b32 v43, v174, v175 offset0:132 offset1:198
	s_waitcnt vmcnt(26)
	ds_write2_b32 v52, v176, v177 offset0:8 offset1:74
	s_waitcnt vmcnt(24)
	ds_write2_b32 v52, v178, v179 offset0:140 offset1:206
	v_add_u32_e32 v43, 0x840, v43
	v_add_u32_e32 v52, 0x400, v43
	s_waitcnt vmcnt(22)
	ds_write2_b32 v43, v180, v181 offset1:66
	s_waitcnt vmcnt(20)
	ds_write2_b32 v43, v182, v183 offset0:132 offset1:198
	s_waitcnt vmcnt(18)
; #define LAS __attribute__((address_space(3)))
; __device__ __forceinline__ unsigned pk2(float lo, float hi) { return pg8::cvt_pk_bf16(lo, hi); }
; __device__ __forceinline__ int rowmap(int mode, int n0) {
;     ...
;     if (mode == 2) { const int bj = n0 >= FFH ? 1 : 0, r = n0 - bj * FFH; return (r >> 7) * 256 + bj * 128 + (r & 127); }
; __device__ __forceinline__ void transpose_item(const float* __restrict__ W, int K, int N, bf16* __restrict__ WT, int mode, LAS float* scr, int item, int lane) {
;     ...
;     for (int i = 0; i < 32; ++i) { const int kk = 2 * i + (lane >> 5); scr[kk * 33 + (lane & 31)] = __builtin_nontemporal_load(W + (size_t)(k0 + kk) * N + n0 + (lane & 31)); }
;     asm volatile("s_waitcnt lgkmcnt(0)" ::: "memory");
;     const int c = lane & 7; const int r0 = rowmap(mode, n0);
; #pragma unroll
;     for (int j = 0; j < 4; ++j) { const int n = (lane >> 3) + 8 * j; const LAS float* s = scr + (8 * c) * 33 + n;
;         u32x4 o; o.x = pk2(s[0 * 33], s[1 * 33]); o.y = pk2(s[2 * 33], s[3 * 33]); o.z = pk2(s[4 * 33], s[5 * 33]); o.w = pk2(s[6 * 33], s[7 * 33]);
;         *(u32x4*)(WT + (size_t)(r0 + n) * K + k0 + 8 * c) = o; }
;     asm volatile("s_waitcnt lgkmcnt(0)" ::: "memory");
	ds_write2_b32 v52, v184, v185 offset0:8 offset1:74
	s_waitcnt vmcnt(16)
	ds_write2_b32 v52, v186, v187 offset0:140 offset1:206
	v_add_u32_e32 v43, 0x840, v43
	v_add_u32_e32 v52, 0x400, v43
	s_waitcnt vmcnt(14)
	ds_write2_b32 v43, v188, v189 offset1:66
	s_waitcnt vmcnt(12)
	ds_write2_b32 v43, v190, v191 offset0:132 offset1:198
	s_waitcnt vmcnt(10)
	ds_write2_b32 v52, v192, v193 offset0:8 offset1:74
	s_waitcnt vmcnt(8)
	ds_write2_b32 v52, v194, v195 offset0:140 offset1:206
	v_add_u32_e32 v43, 0x840, v43
	v_add_u32_e32 v52, 0x400, v43
	s_waitcnt vmcnt(6)
	ds_write2_b32 v43, v196, v197 offset1:66
	s_waitcnt vmcnt(4)
	ds_write2_b32 v43, v198, v199 offset0:132 offset1:198
	s_waitcnt vmcnt(2)
	ds_write2_b32 v52, v218, v219 offset0:8 offset1:74
	s_waitcnt vmcnt(0)
	ds_write2_b32 v52, v220, v221 offset0:140 offset1:206
	v_add_u32_e32 v43, 0x840, v43
	s_movk_i32 s3, 0x57
	s_waitcnt lgkmcnt(0)
	v_cmp_lt_u16_e32 vcc, s3, v42
	ds_read2_b32 v[10:11], v27 offset1:33
	v_mov_b64_e32 v[12:13], s[8:9]
	v_cndmask_b32_e32 v18, 0, v213, vcc
	s_waitcnt lgkmcnt(0)
	v_cvt_pk_bf16_f32 v10, v10, v11
	ds_read2_b32 v[14:15], v27 offset0:66 offset1:99
	v_mad_i64_i32 v[16:17], s[22:23], v8, s52, v[12:13]
	v_add_lshl_u32 v8, v18, v41, 1
	v_and_b32_e32 v19, 0x60, v41
	s_waitcnt lgkmcnt(0)
	v_cvt_pk_bf16_f32 v11, v14, v15
	v_cndmask_b32_e32 v14, 0, v214, vcc
	v_and_b32_e32 v8, 0xffffff00, v8
	v_lshlrev_b32_e32 v160, 1, v9
	v_or3_b32 v18, v19, v14, v8
	v_lshl_add_u64 v[8:9], v[16:17], 0, v[160:161]
	v_lshlrev_b32_e32 v160, 1, v4
	v_lshl_add_u64 v[16:17], v[8:9], 0, v[160:161]
	v_or_b32_e32 v8, v18, v26
	ds_read2_b32 v[12:13], v27 offset0:132 offset1:165
	v_ashrrev_i32_e32 v9, 31, v8
	s_waitcnt lgkmcnt(0)
	v_cvt_pk_bf16_f32 v12, v12, v13
	ds_read2_b32 v[14:15], v27 offset0:198 offset1:231
	v_lshlrev_b64 v[8:9], 11, v[8:9]
	s_waitcnt lgkmcnt(0)
	v_cvt_pk_bf16_f32 v13, v14, v15
	ds_read2_b32 v[14:15], v27 offset0:8 offset1:41
	v_lshl_add_u64 v[8:9], v[16:17], 0, v[8:9]
	global_store_dwordx4 v[8:9], v[10:13], off
	s_waitcnt lgkmcnt(0)
	v_cvt_pk_bf16_f32 v8, v14, v15
	v_or_b32_e32 v14, v18, v28
	v_ashrrev_i32_e32 v15, 31, v14
	ds_read2_b32 v[10:11], v27 offset0:74 offset1:107
	v_lshlrev_b64 v[14:15], 11, v[14:15]
	s_waitcnt lgkmcnt(0)
	v_cvt_pk_bf16_f32 v9, v10, v11
	ds_read2_b32 v[10:11], v27 offset0:140 offset1:173
	v_lshl_add_u64 v[14:15], v[16:17], 0, v[14:15]
	s_waitcnt lgkmcnt(0)
	v_cvt_pk_bf16_f32 v10, v10, v11
	ds_read2_b32 v[12:13], v27 offset0:206 offset1:239
	s_waitcnt lgkmcnt(0)
	v_cvt_pk_bf16_f32 v11, v12, v13
	global_store_dwordx4 v[14:15], v[8:11], off
	v_or_b32_e32 v14, v18, v29
	ds_read2_b32 v[12:13], v27 offset0:16 offset1:49
	s_waitcnt lgkmcnt(0)
	v_cvt_pk_bf16_f32 v8, v12, v13
	ds_read2_b32 v[10:11], v27 offset0:82 offset1:115
	v_ashrrev_i32_e32 v15, 31, v14
	s_waitcnt lgkmcnt(0)
	v_cvt_pk_bf16_f32 v9, v10, v11
	ds_read2_b32 v[10:11], v27 offset0:148 offset1:181
	v_lshlrev_b64 v[14:15], 11, v[14:15]
	s_waitcnt lgkmcnt(0)
	v_cvt_pk_bf16_f32 v10, v10, v11
	ds_read2_b32 v[12:13], v27 offset0:214 offset1:247
	s_waitcnt lgkmcnt(0)
	v_cvt_pk_bf16_f32 v11, v12, v13
	v_lshl_add_u64 v[14:15], v[16:17], 0, v[14:15]
	ds_read2_b32 v[12:13], v27 offset0:24 offset1:57
	global_store_dwordx4 v[14:15], v[8:11], off
	v_or_b32_e32 v14, v18, v30
	v_ashrrev_i32_e32 v15, 31, v14
	s_waitcnt lgkmcnt(0)
	v_cvt_pk_bf16_f32 v8, v12, v13
	ds_read2_b32 v[10:11], v27 offset0:90 offset1:123
	s_waitcnt lgkmcnt(0)
	v_cvt_pk_bf16_f32 v9, v10, v11
	ds_read2_b32 v[10:11], v27 offset0:156 offset1:189
	s_waitcnt lgkmcnt(0)
	v_cvt_pk_bf16_f32 v10, v10, v11
	ds_read2_b32 v[12:13], v27 offset0:222 offset1:255
	v_lshlrev_b64 v[14:15], 11, v[14:15]
	s_waitcnt lgkmcnt(0)
	v_cvt_pk_bf16_f32 v11, v12, v13
	v_lshl_add_u64 v[12:13], v[16:17], 0, v[14:15]
	global_store_dwordx4 v[12:13], v[8:11], off
	s_waitcnt lgkmcnt(0)

; __device__ __forceinline__ void transpose_item(const float* __restrict__ W, int K, int N, bf16* __restrict__ WT, int mode, LAS float* scr, int item, int lane) {
;     const int nblk = N / 32, kb = item / nblk, nb = item % nblk, k0 = 64 * kb, n0 = 32 * nb;
; #pragma unroll 8
;     for (int i = 0; i < 32; ++i) { const int kk = 2 * i + (lane >> 5); scr[kk * 33 + (lane & 31)] = __builtin_nontemporal_load(W + (size_t)(k0 + kk) * N + n0 + (lane & 31)); }
;     asm volatile("s_waitcnt lgkmcnt(0)" ::: "memory");
.LBB0_390:
	v_lshl_add_u64 v[44:45], v[24:25], 0, s[20:21]
	v_lshl_add_u64 v[46:47], v[22:23], 0, s[20:21]
	v_lshl_add_u64 v[48:49], v[20:21], 0, s[20:21]
	v_lshl_add_u64 v[50:51], v[18:19], 0, s[20:21]
	v_lshl_add_u64 v[52:53], v[16:17], 0, s[20:21]
	v_lshl_add_u64 v[54:55], v[14:15], 0, s[20:21]
	v_lshl_add_u64 v[56:57], v[12:13], 0, s[20:21]
	v_lshl_add_u64 v[58:59], v[10:11], 0, s[20:21]
	global_load_dword v172, v[44:45], off nt
	s_nop 0
	global_load_dword v173, v[46:47], off nt
	global_load_dword v174, v[48:49], off nt
	s_nop 0
	global_load_dword v175, v[50:51], off nt
	global_load_dword v176, v[52:53], off nt
	global_load_dword v177, v[54:55], off nt
	global_load_dword v178, v[56:57], off nt
	s_nop 0
	global_load_dword v179, v[58:59], off nt
	s_add_u32 s20, s20, 0x10000
	s_addc_u32 s21, s21, 0
	v_lshl_add_u64 v[44:45], v[24:25], 0, s[20:21]
	v_lshl_add_u64 v[46:47], v[22:23], 0, s[20:21]
	v_lshl_add_u64 v[48:49], v[20:21], 0, s[20:21]
	v_lshl_add_u64 v[50:51], v[18:19], 0, s[20:21]
	v_lshl_add_u64 v[52:53], v[16:17], 0, s[20:21]
	v_lshl_add_u64 v[54:55], v[14:15], 0, s[20:21]
	v_lshl_add_u64 v[56:57], v[12:13], 0, s[20:21]
	v_lshl_add_u64 v[58:59], v[10:11], 0, s[20:21]
	global_load_dword v180, v[44:45], off nt
	s_nop 0
	global_load_dword v181, v[46:47], off nt
	global_load_dword v182, v[48:49], off nt
	s_nop 0
	global_load_dword v183, v[50:51], off nt
	global_load_dword v184, v[52:53], off nt
	global_load_dword v185, v[54:55], off nt
	global_load_dword v186, v[56:57], off nt
	s_nop 0
	global_load_dword v187, v[58:59], off nt
	s_add_u32 s20, s20, 0x10000
	s_addc_u32 s21, s21, 0
	v_lshl_add_u64 v[44:45], v[24:25], 0, s[20:21]
	v_lshl_add_u64 v[46:47], v[22:23], 0, s[20:21]
	v_lshl_add_u64 v[48:49], v[20:21], 0, s[20:21]
	v_lshl_add_u64 v[50:51], v[18:19], 0, s[20:21]
	v_lshl_add_u64 v[52:53], v[16:17], 0, s[20:21]
	v_lshl_add_u64 v[54:55], v[14:15], 0, s[20:21]
	v_lshl_add_u64 v[56:57], v[12:13], 0, s[20:21]
	v_lshl_add_u64 v[58:59], v[10:11], 0, s[20:21]
	global_load_dword v188, v[44:45], off nt
	s_nop 0
	global_load_dword v189, v[46:47], off nt
	global_load_dword v190, v[48:49], off nt
	s_nop 0
	global_load_dword v191, v[50:51], off nt
	global_load_dword v192, v[52:53], off nt
	global_load_dword v193, v[54:55], off nt
	global_load_dword v194, v[56:57], off nt
	s_nop 0
	global_load_dword v195, v[58:59], off nt
	s_add_u32 s20, s20, 0x10000
	s_addc_u32 s21, s21, 0
	v_lshl_add_u64 v[44:45], v[24:25], 0, s[20:21]
	v_lshl_add_u64 v[46:47], v[22:23], 0, s[20:21]
	v_lshl_add_u64 v[48:49], v[20:21], 0, s[20:21]
	v_lshl_add_u64 v[50:51], v[18:19], 0, s[20:21]
	v_lshl_add_u64 v[52:53], v[16:17], 0, s[20:21]
	v_lshl_add_u64 v[54:55], v[14:15], 0, s[20:21]
	v_lshl_add_u64 v[56:57], v[12:13], 0, s[20:21]
	v_lshl_add_u64 v[58:59], v[10:11], 0, s[20:21]
	global_load_dword v196, v[44:45], off nt
	s_nop 0
	global_load_dword v197, v[46:47], off nt
	global_load_dword v198, v[48:49], off nt
	s_nop 0
	global_load_dword v199, v[50:51], off nt
	global_load_dword v218, v[52:53], off nt
	global_load_dword v219, v[54:55], off nt
	global_load_dword v220, v[56:57], off nt
	s_nop 0
	global_load_dword v221, v[58:59], off nt
	s_add_u32 s20, s20, 0x10000
	s_addc_u32 s21, s21, 0
	v_add_u32_e32 v51, 0x400, v42
	s_waitcnt vmcnt(30)
	ds_write2_b32 v42, v172, v173 offset1:66
	s_waitcnt vmcnt(28)
	ds_write2_b32 v42, v174, v175 offset0:132 offset1:198
	s_waitcnt vmcnt(26)
	ds_write2_b32 v51, v176, v177 offset0:8 offset1:74
	s_waitcnt vmcnt(24)
	ds_write2_b32 v51, v178, v179 offset0:140 offset1:206
	v_add_u32_e32 v42, 0x840, v42
	v_add_u32_e32 v51, 0x400, v42
	s_waitcnt vmcnt(22)
; #define LAS __attribute__((address_space(3)))
; __device__ __forceinline__ unsigned pk2(float lo, float hi) { return pg8::cvt_pk_bf16(lo, hi); }
; __device__ __forceinline__ void transpose_item(const float* __restrict__ W, int K, int N, bf16* __restrict__ WT, int mode, LAS float* scr, int item, int lane) {
;     ...
;     for (int i = 0; i < 32; ++i) { const int kk = 2 * i + (lane >> 5); scr[kk * 33 + (lane & 31)] = __builtin_nontemporal_load(W + (size_t)(k0 + kk) * N + n0 + (lane & 31)); }
;     asm volatile("s_waitcnt lgkmcnt(0)" ::: "memory");
;     const int c = lane & 7; const int r0 = rowmap(mode, n0);
; #pragma unroll
;     for (int j = 0; j < 4; ++j) { const int n = (lane >> 3) + 8 * j; const LAS float* s = scr + (8 * c) * 33 + n;
;         u32x4 o; o.x = pk2(s[0 * 33], s[1 * 33]); o.y = pk2(s[2 * 33], s[3 * 33]); o.z = pk2(s[4 * 33], s[5 * 33]); o.w = pk2(s[6 * 33], s[7 * 33]);
;         *(u32x4*)(WT + (size_t)(r0 + n) * K + k0 + 8 * c) = o; }
;     asm volatile("s_waitcnt lgkmcnt(0)" ::: "memory");
	ds_write2_b32 v42, v180, v181 offset1:66
	s_waitcnt vmcnt(20)
	ds_write2_b32 v42, v182, v183 offset0:132 offset1:198
	s_waitcnt vmcnt(18)
	ds_write2_b32 v51, v184, v185 offset0:8 offset1:74
	s_waitcnt vmcnt(16)
	ds_write2_b32 v51, v186, v187 offset0:140 offset1:206
	v_add_u32_e32 v42, 0x840, v42
	v_add_u32_e32 v51, 0x400, v42
	s_waitcnt vmcnt(14)
	ds_write2_b32 v42, v188, v189 offset1:66
	s_waitcnt vmcnt(12)
	ds_write2_b32 v42, v190, v191 offset0:132 offset1:198
	s_waitcnt vmcnt(10)
	ds_write2_b32 v51, v192, v193 offset0:8 offset1:74
	s_waitcnt vmcnt(8)
	ds_write2_b32 v51, v194, v195 offset0:140 offset1:206
	v_add_u32_e32 v42, 0x840, v42
	v_add_u32_e32 v51, 0x400, v42
	s_waitcnt vmcnt(6)
	ds_write2_b32 v42, v196, v197 offset1:66
	s_waitcnt vmcnt(4)
	ds_write2_b32 v42, v198, v199 offset0:132 offset1:198
	s_waitcnt vmcnt(2)
	ds_write2_b32 v51, v218, v219 offset0:8 offset1:74
	s_waitcnt vmcnt(0)
	ds_write2_b32 v51, v220, v221 offset0:140 offset1:206
	v_add_u32_e32 v42, 0x840, v42
	s_waitcnt lgkmcnt(0)
	ds_read2_b32 v[10:11], v27 offset1:33
	v_lshlrev_b32_e32 v14, 5, v3
	v_lshlrev_b64 v[8:9], 21, v[8:9]
	s_waitcnt lgkmcnt(0)
	v_cvt_pk_bf16_f32 v10, v10, v11
	ds_read2_b32 v[12:13], v27 offset0:66 offset1:99
	v_lshlrev_b32_e32 v160, 1, v41
	v_and_b32_e32 v18, 0x3e0, v14
	v_lshl_add_u64 v[8:9], s[10:11], 0, v[8:9]
	s_waitcnt lgkmcnt(0)
	v_cvt_pk_bf16_f32 v11, v12, v13
	ds_read2_b32 v[12:13], v27 offset0:132 offset1:165
	v_lshl_add_u64 v[8:9], v[8:9], 0, v[160:161]
	v_lshlrev_b32_e32 v160, 1, v4
	v_or_b32_e32 v19, v18, v26
	s_waitcnt lgkmcnt(0)
	v_cvt_pk_bf16_f32 v12, v12, v13
	ds_read2_b32 v[14:15], v27 offset0:198 offset1:231
	v_lshl_add_u64 v[16:17], v[8:9], 0, v[160:161]
	v_lshlrev_b32_e32 v160, 11, v19
	s_waitcnt lgkmcnt(0)
	v_cvt_pk_bf16_f32 v13, v14, v15
	ds_read2_b32 v[14:15], v27 offset0:8 offset1:41
	v_lshl_add_u64 v[8:9], v[16:17], 0, v[160:161]
	global_store_dwordx4 v[8:9], v[10:13], off
	s_waitcnt lgkmcnt(0)
	v_cvt_pk_bf16_f32 v8, v14, v15
	ds_read2_b32 v[10:11], v27 offset0:74 offset1:107
	v_or_b32_e32 v14, v18, v28
	s_waitcnt lgkmcnt(0)
	v_cvt_pk_bf16_f32 v9, v10, v11
	ds_read2_b32 v[10:11], v27 offset0:140 offset1:173
	v_lshlrev_b32_e32 v160, 11, v14
	s_waitcnt lgkmcnt(0)
	v_cvt_pk_bf16_f32 v10, v10, v11
	ds_read2_b32 v[12:13], v27 offset0:206 offset1:239
	s_waitcnt lgkmcnt(0)
	v_cvt_pk_bf16_f32 v11, v12, v13
	v_lshl_add_u64 v[14:15], v[16:17], 0, v[160:161]
	ds_read2_b32 v[12:13], v27 offset0:16 offset1:49
	global_store_dwordx4 v[14:15], v[8:11], off
	v_or_b32_e32 v14, v18, v29
	v_lshlrev_b32_e32 v160, 11, v14
	s_waitcnt lgkmcnt(0)
	v_cvt_pk_bf16_f32 v8, v12, v13
	ds_read2_b32 v[10:11], v27 offset0:82 offset1:115
	s_waitcnt lgkmcnt(0)
	v_cvt_pk_bf16_f32 v9, v10, v11
	ds_read2_b32 v[10:11], v27 offset0:148 offset1:181
	s_waitcnt lgkmcnt(0)
	v_cvt_pk_bf16_f32 v10, v10, v11
	ds_read2_b32 v[12:13], v27 offset0:214 offset1:247
	s_waitcnt lgkmcnt(0)
	v_cvt_pk_bf16_f32 v11, v12, v13
	v_lshl_add_u64 v[14:15], v[16:17], 0, v[160:161]
	ds_read2_b32 v[12:13], v27 offset0:24 offset1:57
	global_store_dwordx4 v[14:15], v[8:11], off
	s_waitcnt lgkmcnt(0)
	s_nop 0
	v_cvt_pk_bf16_f32 v8, v12, v13
	ds_read2_b32 v[10:11], v27 offset0:90 offset1:123
	s_waitcnt lgkmcnt(0)
	v_cvt_pk_bf16_f32 v9, v10, v11
	ds_read2_b32 v[10:11], v27 offset0:156 offset1:189
	s_waitcnt lgkmcnt(0)
	v_cvt_pk_bf16_f32 v10, v10, v11
	v_or_b32_e32 v11, v18, v30
	ds_read2_b32 v[12:13], v27 offset0:222 offset1:255
	v_lshlrev_b32_e32 v160, 11, v11
	s_waitcnt lgkmcnt(0)
	v_cvt_pk_bf16_f32 v11, v12, v13
	v_lshl_add_u64 v[12:13], v[16:17], 0, v[160:161]
	global_store_dwordx4 v[12:13], v[8:11], off
	s_waitcnt lgkmcnt(0)

; __device__ __forceinline__ void transpose_item(const float* __restrict__ W, int K, int N, bf16* __restrict__ WT, int mode, LAS float* scr, int item, int lane) {
;     const int nblk = N / 32, kb = item / nblk, nb = item % nblk, k0 = 64 * kb, n0 = 32 * nb;
; #pragma unroll 8
;     for (int i = 0; i < 32; ++i) { const int kk = 2 * i + (lane >> 5); scr[kk * 33 + (lane & 31)] = __builtin_nontemporal_load(W + (size_t)(k0 + kk) * N + n0 + (lane & 31)); }
;     asm volatile("s_waitcnt lgkmcnt(0)" ::: "memory");
.LBB0_395:
	v_add_u32_e32 v18, s3, v11
	v_add_u32_e32 v19, 2, v18
	v_add_u32_e32 v20, 4, v18
	v_add_u32_e32 v22, 6, v18
	v_mad_i64_i32 v[16:17], s[16:17], v18, s59, v[14:15]
	v_add_u32_e32 v24, 8, v18
	v_add_u32_e32 v41, 10, v18
	v_add_u32_e32 v44, 12, v18
	v_add_u32_e32 v46, 14, v18
	v_mad_i64_i32 v[18:19], s[16:17], v19, s59, v[14:15]
	v_mad_i64_i32 v[20:21], s[16:17], v20, s59, v[14:15]
	v_mad_i64_i32 v[22:23], s[16:17], v22, s59, v[14:15]
	v_mad_i64_i32 v[24:25], s[16:17], v24, s59, v[14:15]
	v_mad_i64_i32 v[42:43], s[16:17], v41, s59, v[14:15]
	v_mad_i64_i32 v[44:45], s[16:17], v44, s59, v[14:15]
	v_mad_i64_i32 v[46:47], s[16:17], v46, s59, v[14:15]
	global_load_dword v172, v[16:17], off nt
	s_nop 0
	global_load_dword v173, v[18:19], off nt
	s_nop 0
	global_load_dword v174, v[20:21], off nt
	global_load_dword v175, v[22:23], off nt
	s_nop 0
	global_load_dword v176, v[24:25], off nt
	global_load_dword v177, v[42:43], off nt
	global_load_dword v178, v[44:45], off nt
	global_load_dword v179, v[46:47], off nt
	s_add_i32 s3, s3, 16
	v_add_u32_e32 v18, s3, v11
	v_add_u32_e32 v19, 2, v18
	v_add_u32_e32 v20, 4, v18
	v_add_u32_e32 v22, 6, v18
	v_mad_i64_i32 v[16:17], s[16:17], v18, s59, v[14:15]
	v_add_u32_e32 v24, 8, v18
	v_add_u32_e32 v41, 10, v18
	v_add_u32_e32 v44, 12, v18
	v_add_u32_e32 v46, 14, v18
	v_mad_i64_i32 v[18:19], s[16:17], v19, s59, v[14:15]
	v_mad_i64_i32 v[20:21], s[16:17], v20, s59, v[14:15]
	v_mad_i64_i32 v[22:23], s[16:17], v22, s59, v[14:15]
	v_mad_i64_i32 v[24:25], s[16:17], v24, s59, v[14:15]
	v_mad_i64_i32 v[42:43], s[16:17], v41, s59, v[14:15]
	v_mad_i64_i32 v[44:45], s[16:17], v44, s59, v[14:15]
	v_mad_i64_i32 v[46:47], s[16:17], v46, s59, v[14:15]
	global_load_dword v180, v[16:17], off nt
	s_nop 0
	global_load_dword v181, v[18:19], off nt
	s_nop 0
	global_load_dword v182, v[20:21], off nt
	global_load_dword v183, v[22:23], off nt
	s_nop 0
	global_load_dword v184, v[24:25], off nt
	global_load_dword v185, v[42:43], off nt
	global_load_dword v186, v[44:45], off nt
	global_load_dword v187, v[46:47], off nt
	s_add_i32 s3, s3, 16
	v_add_u32_e32 v18, s3, v11
	v_add_u32_e32 v19, 2, v18
	v_add_u32_e32 v20, 4, v18
	v_add_u32_e32 v22, 6, v18
	v_mad_i64_i32 v[16:17], s[16:17], v18, s59, v[14:15]
	v_add_u32_e32 v24, 8, v18
	v_add_u32_e32 v41, 10, v18
	v_add_u32_e32 v44, 12, v18
	v_add_u32_e32 v46, 14, v18
	v_mad_i64_i32 v[18:19], s[16:17], v19, s59, v[14:15]
	v_mad_i64_i32 v[20:21], s[16:17], v20, s59, v[14:15]
	v_mad_i64_i32 v[22:23], s[16:17], v22, s59, v[14:15]
	v_mad_i64_i32 v[24:25], s[16:17], v24, s59, v[14:15]
	v_mad_i64_i32 v[42:43], s[16:17], v41, s59, v[14:15]
	v_mad_i64_i32 v[44:45], s[16:17], v44, s59, v[14:15]
	v_mad_i64_i32 v[46:47], s[16:17], v46, s59, v[14:15]
	global_load_dword v188, v[16:17], off nt
	s_nop 0
	global_load_dword v189, v[18:19], off nt
	s_nop 0
	global_load_dword v190, v[20:21], off nt
	global_load_dword v191, v[22:23], off nt
	s_nop 0
	global_load_dword v192, v[24:25], off nt
	global_load_dword v193, v[42:43], off nt
	global_load_dword v194, v[44:45], off nt
	global_load_dword v195, v[46:47], off nt
	s_add_i32 s3, s3, 16
	v_add_u32_e32 v18, s3, v11
	v_add_u32_e32 v19, 2, v18
	v_add_u32_e32 v20, 4, v18
	v_add_u32_e32 v22, 6, v18
	v_mad_i64_i32 v[16:17], s[16:17], v18, s59, v[14:15]
	v_add_u32_e32 v24, 8, v18
	v_add_u32_e32 v41, 10, v18
	v_add_u32_e32 v44, 12, v18
	v_add_u32_e32 v46, 14, v18
	v_mad_i64_i32 v[18:19], s[16:17], v19, s59, v[14:15]
	v_mad_i64_i32 v[20:21], s[16:17], v20, s59, v[14:15]
	v_mad_i64_i32 v[22:23], s[16:17], v22, s59, v[14:15]
	v_mad_i64_i32 v[24:25], s[16:17], v24, s59, v[14:15]
	v_mad_i64_i32 v[42:43], s[16:17], v41, s59, v[14:15]
	v_mad_i64_i32 v[44:45], s[16:17], v44, s59, v[14:15]
	v_mad_i64_i32 v[46:47], s[16:17], v46, s59, v[14:15]
	global_load_dword v196, v[16:17], off nt
	s_nop 0
	global_load_dword v197, v[18:19], off nt
	s_nop 0
	global_load_dword v198, v[20:21], off nt
	global_load_dword v199, v[22:23], off nt
	s_nop 0
	global_load_dword v218, v[24:25], off nt
	global_load_dword v219, v[42:43], off nt
	global_load_dword v220, v[44:45], off nt
	global_load_dword v221, v[46:47], off nt
	s_add_i32 s3, s3, 16
	v_add_u32_e32 v24, 0x400, v13
	s_waitcnt vmcnt(30)
	ds_write2_b32 v13, v172, v173 offset1:66
	s_waitcnt vmcnt(28)
; #define LAS __attribute__((address_space(3)))
; __device__ __forceinline__ unsigned pk2(float lo, float hi) { return pg8::cvt_pk_bf16(lo, hi); }
; __device__ __forceinline__ int rowmap(int mode, int n0) {
;     if (mode == 1) { const int pn = n0 >> 8, q = n0 & 255; return pn * 256 + 128 * ((q & 63) >> 5) + 32 * (q >> 6); }
; __device__ __forceinline__ void transpose_item(const float* __restrict__ W, int K, int N, bf16* __restrict__ WT, int mode, LAS float* scr, int item, int lane) {
;     ...
;     for (int i = 0; i < 32; ++i) { const int kk = 2 * i + (lane >> 5); scr[kk * 33 + (lane & 31)] = __builtin_nontemporal_load(W + (size_t)(k0 + kk) * N + n0 + (lane & 31)); }
;     asm volatile("s_waitcnt lgkmcnt(0)" ::: "memory");
;     const int c = lane & 7; const int r0 = rowmap(mode, n0);
; #pragma unroll
;     for (int j = 0; j < 4; ++j) { const int n = (lane >> 3) + 8 * j; const LAS float* s = scr + (8 * c) * 33 + n;
;         u32x4 o; o.x = pk2(s[0 * 33], s[1 * 33]); o.y = pk2(s[2 * 33], s[3 * 33]); o.z = pk2(s[4 * 33], s[5 * 33]); o.w = pk2(s[6 * 33], s[7 * 33]);
;         *(u32x4*)(WT + (size_t)(r0 + n) * K + k0 + 8 * c) = o; }
;     asm volatile("s_waitcnt lgkmcnt(0)" ::: "memory");
; __device__ __forceinline__ void convert_weights(ArgP A, unsigned char* lds_g, int gw, int NGW, int l0, int l1, int lane, int wave) {
;     ...
;     for (int it = l0 * PER_L + gw; it < l1 * PER_L; it += NGW) {
;         const int l = it / PER_L; int r = it - l * PER_L;
;         if (r < I_IN) { transpose_item(A->w_in + (size_t)l * DM * INW, DM, INW, (bf16*)(ws + WS_WIN) + (size_t)l * INW * DM, 1, scr, r, lane); continue; } r -= I_IN;
;         if (r < I_OUT) { transpose_item(A->w_out + (size_t)l * DM * DM, DM, DM, (bf16*)(ws + WS_WOUT) + (size_t)l * DM * DM, 0, scr, r, lane); continue; } r -= I_OUT;
;         if (r < I_F1) { transpose_item(A->w_ffn_in + (size_t)l * DM * FF2, DM, FF2, (bf16*)(ws + WS_WF1) + (size_t)l * FF2 * DM, 2, scr, r, lane); continue; } r -= I_F1;
;         transpose_item(A->w_ffn_out + (size_t)l * FFH * DM, FFH, DM, (bf16*)(ws + WS_WF2) + (size_t)l * DM * FFH, 0, scr, r, lane);
;     }
	ds_write2_b32 v13, v174, v175 offset0:132 offset1:198
	s_waitcnt vmcnt(26)
	ds_write2_b32 v24, v176, v177 offset0:8 offset1:74
	s_waitcnt vmcnt(24)
	ds_write2_b32 v24, v178, v179 offset0:140 offset1:206
	v_add_u32_e32 v13, 0x840, v13
	v_add_u32_e32 v24, 0x400, v13
	s_waitcnt vmcnt(22)
	ds_write2_b32 v13, v180, v181 offset1:66
	s_waitcnt vmcnt(20)
	ds_write2_b32 v13, v182, v183 offset0:132 offset1:198
	s_waitcnt vmcnt(18)
	ds_write2_b32 v24, v184, v185 offset0:8 offset1:74
	s_waitcnt vmcnt(16)
	ds_write2_b32 v24, v186, v187 offset0:140 offset1:206
	v_add_u32_e32 v13, 0x840, v13
	v_add_u32_e32 v24, 0x400, v13
	s_waitcnt vmcnt(14)
	ds_write2_b32 v13, v188, v189 offset1:66
	s_waitcnt vmcnt(12)
	ds_write2_b32 v13, v190, v191 offset0:132 offset1:198
	s_waitcnt vmcnt(10)
	ds_write2_b32 v24, v192, v193 offset0:8 offset1:74
	s_waitcnt vmcnt(8)
	ds_write2_b32 v24, v194, v195 offset0:140 offset1:206
	v_add_u32_e32 v13, 0x840, v13
	v_add_u32_e32 v24, 0x400, v13
	s_waitcnt vmcnt(6)
	ds_write2_b32 v13, v196, v197 offset1:66
	s_waitcnt vmcnt(4)
	ds_write2_b32 v13, v198, v199 offset0:132 offset1:198
	s_waitcnt vmcnt(2)
	ds_write2_b32 v24, v218, v219 offset0:8 offset1:74
	s_waitcnt vmcnt(0)
	ds_write2_b32 v24, v220, v221 offset0:140 offset1:206
	v_add_u32_e32 v13, 0x840, v13
	s_waitcnt lgkmcnt(0)
	ds_read2_b32 v[14:15], v27 offset1:33
	v_mul_hi_i32_i24_e32 v17, 0x380000, v8
	s_waitcnt lgkmcnt(0)
	v_cvt_pk_bf16_f32 v14, v14, v15
	ds_read2_b32 v[18:19], v27 offset0:66 offset1:99
	v_mul_i32_i24_e32 v16, 0x380000, v8
	v_lshlrev_b32_e32 v21, 7, v9
	v_lshrrev_b32_e32 v22, 1, v12
	v_and_b32_e32 v20, 0xffffff00, v12
	s_waitcnt lgkmcnt(0)
	v_cvt_pk_bf16_f32 v15, v18, v19
	ds_read2_b32 v[8:9], v27 offset0:132 offset1:165
	v_lshl_add_u64 v[12:13], s[28:29], 0, v[16:17]
	v_and_b32_e32 v17, 0x80, v21
	v_and_b32_e32 v18, 0x60, v22
	s_waitcnt lgkmcnt(0)
	v_cvt_pk_bf16_f32 v16, v8, v9
	ds_read2_b32 v[8:9], v27 offset0:198 offset1:231
	v_or3_b32 v18, v17, v20, v18
	v_ashrrev_i32_e32 v11, 31, v10
	s_waitcnt lgkmcnt(0)
	v_cvt_pk_bf16_f32 v17, v8, v9
	v_or_b32_e32 v8, v18, v26
	v_lshlrev_b32_e32 v160, 1, v4
	v_lshl_add_u64 v[10:11], v[10:11], 1, v[12:13]
	v_ashrrev_i32_e32 v9, 31, v8
	v_lshl_add_u64 v[12:13], v[10:11], 0, v[160:161]
	v_lshlrev_b64 v[8:9], 11, v[8:9]
	v_lshl_add_u64 v[8:9], v[12:13], 0, v[8:9]
	global_store_dwordx4 v[8:9], v[14:17], off
	ds_read2_b32 v[10:11], v27 offset0:8 offset1:41
	s_waitcnt lgkmcnt(0)
	v_cvt_pk_bf16_f32 v8, v10, v11
	ds_read2_b32 v[10:11], v27 offset0:74 offset1:107
	v_or_b32_e32 v16, v18, v28
	v_ashrrev_i32_e32 v17, 31, v16
	v_lshlrev_b64 v[16:17], 11, v[16:17]
	s_waitcnt lgkmcnt(0)
	v_cvt_pk_bf16_f32 v9, v10, v11
	ds_read2_b32 v[10:11], v27 offset0:140 offset1:173
	v_lshl_add_u64 v[16:17], v[12:13], 0, v[16:17]
	s_waitcnt lgkmcnt(0)
	v_cvt_pk_bf16_f32 v10, v10, v11
	ds_read2_b32 v[14:15], v27 offset0:206 offset1:239
	s_waitcnt lgkmcnt(0)
	v_cvt_pk_bf16_f32 v11, v14, v15
	global_store_dwordx4 v[16:17], v[8:11], off
	v_or_b32_e32 v16, v18, v29
	v_ashrrev_i32_e32 v17, 31, v16
	ds_read2_b32 v[14:15], v27 offset0:16 offset1:49
	s_waitcnt lgkmcnt(0)
	v_cvt_pk_bf16_f32 v8, v14, v15
	ds_read2_b32 v[10:11], v27 offset0:82 offset1:115
	v_lshlrev_b64 v[16:17], 11, v[16:17]
	s_waitcnt lgkmcnt(0)
	v_cvt_pk_bf16_f32 v9, v10, v11
	ds_read2_b32 v[10:11], v27 offset0:148 offset1:181
	v_lshl_add_u64 v[16:17], v[12:13], 0, v[16:17]
	s_waitcnt lgkmcnt(0)
	v_cvt_pk_bf16_f32 v10, v10, v11
	ds_read2_b32 v[14:15], v27 offset0:214 offset1:247
	s_waitcnt lgkmcnt(0)
	v_cvt_pk_bf16_f32 v11, v14, v15
	global_store_dwordx4 v[16:17], v[8:11], off
	v_or_b32_e32 v16, v18, v30
	v_ashrrev_i32_e32 v17, 31, v16
	ds_read2_b32 v[14:15], v27 offset0:24 offset1:57
	s_waitcnt lgkmcnt(0)
	v_cvt_pk_bf16_f32 v8, v14, v15
	ds_read2_b32 v[10:11], v27 offset0:90 offset1:123
	v_lshlrev_b64 v[16:17], 11, v[16:17]
	s_waitcnt lgkmcnt(0)
	v_cvt_pk_bf16_f32 v9, v10, v11
	ds_read2_b32 v[10:11], v27 offset0:156 offset1:189
	v_lshl_add_u64 v[12:13], v[12:13], 0, v[16:17]
	s_waitcnt lgkmcnt(0)
	v_cvt_pk_bf16_f32 v10, v10, v11
	ds_read2_b32 v[14:15], v27 offset0:222 offset1:255
	s_waitcnt lgkmcnt(0)
	v_cvt_pk_bf16_f32 v11, v14, v15
	global_store_dwordx4 v[12:13], v[8:11], off
	s_waitcnt lgkmcnt(0)
	s_branch .LBB0_376
